# qkv conv: workgroup takes two whole chunks, token-major K/V copies assembled in LDS and written as whole lines; row prefetch; (plus scan DMA, prep2)
# speedup vs baseline: 1.0323x; 1.0212x over previous
; __device__ __forceinline__ void phase_qkv(const Args& a) {
;     const int tid = threadIdx.x, lane = tid & 63, wave = tid >> 6;
;     const bf16_t* proj = (const bf16_t*)(a.ws + WS_PROJ); const float* cw = a.in[3];
;     for (int item = blockIdx.x * 8 + wave; item < 6144; item += gridDim.x * 8) {
;         const int part = item % 3, rg = item / 3, rowA = rg * 16, pos0 = rowA & 2047, ch0 = part * 512 + 8 * lane;
;         float w[4][8];
; #pragma unroll
;         for (int i = 0; i < 4; ++i) { const f32x4 w0 = *(const f32x4*)(cw + i * 1536 + ch0), w1 = *(const f32x4*)(cw + i * 1536 + ch0 + 4);
;             w[i][0] = w0[0]; w[i][1] = w0[1]; w[i][2] = w0[2]; w[i][3] = w0[3]; w[i][4] = w1[0]; w[i][5] = w1[1]; w[i][6] = w1[2]; w[i][7] = w1[3]; }
;         u32x4 R[19];
; #pragma unroll
;         for (int j = 0; j < 19; ++j) { const int dr = j - 3; const int rr = (pos0 + dr >= 0) ? rowA + dr : rowA; R[j] = *(const u32x4*)(proj + (size_t)rr * NPROJ + ch0); }
;         bf16_t* dst = (bf16_t*)(a.ws + (part == 0 ? WS_QB : WS_KB)) + (size_t)rowA * 512 + 8 * lane;
;         const float qsc = (part == 0) ? 0.08838834764831845f : 1.0f;
.LBB0_126:
	s_or_b64 exec, exec, s[0:1]
	v_readlane_b32 s0, v253, 17
	s_bitcmp0_b32 s0, 2
	v_lshrrev_b32_e32 v153, 6, v152
	s_waitcnt lgkmcnt(0)
	s_barrier
	s_cbranch_scc1 .LBB0_197
	v_readlane_b32 s42, v253, 7
	v_readlane_b32 s43, v253, 8
	v_lshlrev_b32_e32 v248, 4, v152
	v_add_u32_e32 v249, 0x2000, v248
	v_add_u32_e32 v250, 0x4000, v248
	s_nop 4
	global_load_dwordx4 v[172:175], v248, s[42:43]
	global_load_dwordx4 v[176:179], v249, s[42:43]
	global_load_dwordx4 v[180:183], v250, s[42:43]
	v_add_u32_e32 v249, 0x20200, v248
	s_waitcnt vmcnt(0)
	ds_write_b128 v249, v[172:175]
	ds_write_b128 v249, v[176:179] offset:8192
	ds_write_b128 v249, v[180:183] offset:16384
	s_waitcnt lgkmcnt(0)
	s_barrier
	v_and_b32_e32 v248, 63, v152
	v_lshlrev_b32_e32 v248, 4, v248
	v_lshl_add_u32 v96, s82, 3, v153
	s_nop 1
	v_readfirstlane_b32 s86, v96
	v_mul_u32_u24_e32 v96, 3, v96
	s_movk_i32 s0, 0x1800
	v_cmp_gt_i32_e32 vcc, s0, v96
	s_and_saveexec_b64 s[6:7], vcc
	s_cbranch_execz .LBB0_196
	v_lshlrev_b32_e32 v0, 3, v152
	v_lshlrev_b32_e32 v1, 9, v153
	v_and_b32_e32 v0, 0x1f8, v0
	v_mov_b32_e32 v99, 0
	v_lshl_add_u32 v1, s82, 12, v1
	v_lshlrev_b32_e32 v100, 7, v0
	v_mov_b32_e32 v101, v99
	s_mov_b32 s20, 1
	v_lshl_add_u32 v102, v96, 9, v0
	s_movk_i32 s21, 0x200
	s_mov_b64 s[8:9], 0
	s_mov_b32 s22, 0x55555556
	s_movk_i32 s23, 0xfa00
	s_mov_b64 s[10:11], 0x1800
	s_movk_i32 s24, 0x1000
	s_mov_b64 s[12:13], 0x3000
	s_movk_i32 s25, 0x3000
	s_mov_b64 s[14:15], 0x4800
	s_movk_i32 s26, 0x4000
	s_movk_i32 s27, 0x1400
	v_mov_b32_e32 v97, 0x3db504f3
	s_mov_b32 s28, 0xffff0000
	s_mov_b32 s29, 0x800000
	v_lshlrev_b32_e32 v104, 1, v0
	s_movk_i32 s30, 0x17ff
	v_mov_b32_e32 v103, 0x12000000
	v_bfrev_b32_e32 v162, 8
	v_bfrev_b32_e32 v163, 32
	v_bfrev_b32_e32 v164, 64
	v_readfirstlane_b32 s90, v96
	v_add_u32_e32 v251, 2, v96
	s_mov_b32 s88, 0
	s_mov_b32 s101, 0
	s_mov_b32 s91, s90
	s_mul_hi_u32 s92, s91, 0x55555556
	s_mul_i32 s93, s92, 3
	s_sub_u32 s93, s91, s93
	s_mul_i32 s94, s92, 0x14000
	s_lshl_b32 s95, s93, 10
	s_add_u32 s94, s94, s95
	s_add_u32 s96, s2, s94
	s_addc_u32 s97, s3, 0
	s_and_b32 s95, s92, 0x7f
	s_cmp_eq_u32 s95, 0
	s_cselect_b32 s95, 0, 0x1400
	s_mul_i32 s100, s95, 3
	s_sub_u32 s98, s96, s100
	s_subb_u32 s99, s97, 0
	global_load_dwordx4 v[172:175], v248, s[98:99]
	s_add_u32 s98, s98, s95
	s_addc_u32 s99, s99, 0
	global_load_dwordx4 v[176:179], v248, s[98:99]
	s_add_u32 s98, s98, s95
	s_addc_u32 s99, s99, 0
	global_load_dwordx4 v[180:183], v248, s[98:99]
	global_load_dwordx4 v[184:187], v248, s[96:97]
	s_add_u32 s96, s96, 0x1400
	s_addc_u32 s97, s97, 0
	global_load_dwordx4 v[188:191], v248, s[96:97]
	s_add_u32 s96, s96, 0x1400
	s_addc_u32 s97, s97, 0
	global_load_dwordx4 v[192:195], v248, s[96:97]
	s_add_u32 s96, s96, 0x1400
	s_addc_u32 s97, s97, 0
	global_load_dwordx4 v[196:199], v248, s[96:97]
	s_add_u32 s96, s96, 0x1400
	s_addc_u32 s97, s97, 0
	global_load_dwordx4 v[200:203], v248, s[96:97]
	s_add_u32 s96, s96, 0x1400
	s_addc_u32 s97, s97, 0
	global_load_dwordx4 v[204:207], v248, s[96:97]
	s_add_u32 s96, s96, 0x1400
	s_addc_u32 s97, s97, 0
	global_load_dwordx4 v[208:211], v248, s[96:97]
	s_add_u32 s96, s96, 0x1400
	s_addc_u32 s97, s97, 0
	global_load_dwordx4 v[212:215], v248, s[96:97]
	s_add_u32 s96, s96, 0x1400
	s_addc_u32 s97, s97, 0
	global_load_dwordx4 v[216:219], v248, s[96:97]
	s_add_u32 s96, s96, 0x1400
	s_addc_u32 s97, s97, 0
	global_load_dwordx4 v[220:223], v248, s[96:97]
	s_add_u32 s96, s96, 0x1400
	s_addc_u32 s97, s97, 0
	global_load_dwordx4 v[224:227], v248, s[96:97]
	s_add_u32 s96, s96, 0x1400
	s_addc_u32 s97, s97, 0
	global_load_dwordx4 v[228:231], v248, s[96:97]
	s_add_u32 s96, s96, 0x1400
	s_addc_u32 s97, s97, 0
	global_load_dwordx4 v[232:235], v248, s[96:97]
	s_add_u32 s96, s96, 0x1400
	s_addc_u32 s97, s97, 0
	global_load_dwordx4 v[236:239], v248, s[96:97]
	s_add_u32 s96, s96, 0x1400
	s_addc_u32 s97, s97, 0
	global_load_dwordx4 v[240:243], v248, s[96:97]
	s_add_u32 s96, s96, 0x1400
	s_addc_u32 s97, s97, 0
	global_load_dwordx4 v[244:247], v248, s[96:97]
	s_branch .LBB0_130
; __device__ __forceinline__ void phase_qkv(const Args& a) {
;     ...
;     for (int item = blockIdx.x * 8 + wave; item < 6144; item += gridDim.x * 8) {
;         const int part = item % 3, rg = item / 3, rowA = rg * 16, pos0 = rowA & 2047, ch0 = part * 512 + 8 * lane;
;         float w[4][8];
; #pragma unroll
;         for (int i = 0; i < 4; ++i) { const f32x4 w0 = *(const f32x4*)(cw + i * 1536 + ch0), w1 = *(const f32x4*)(cw + i * 1536 + ch0 + 4);
;             w[i][0] = w0[0]; w[i][1] = w0[1]; w[i][2] = w0[2]; w[i][3] = w0[3]; w[i][4] = w1[0]; w[i][5] = w1[1]; w[i][6] = w1[2]; w[i][7] = w1[3]; }
;         u32x4 R[19];
; #pragma unroll
;         for (int j = 0; j < 19; ++j) { const int dr = j - 3; const int rr = (pos0 + dr >= 0) ? rowA + dr : rowA; R[j] = *(const u32x4*)(proj + (size_t)rr * NPROJ + ch0); }
.LBB0_129:
	s_or_b64 exec, exec, s[0:1]
	s_add_u32 s90, s90, s20
	s_add_u32 s88, s88, 1
	v_add_u32_e32 v96, s20, v96
	v_cmp_lt_i32_e32 vcc, v251, v96
	s_or_b64 s[8:9], vcc, s[8:9]
	v_add_u32_e32 v102, s21, v102
	s_andn2_b64 exec, exec, s[8:9]
	s_cbranch_execz .LBB0_196
.LBB0_130:
	v_mul_hi_i32 v0, v96, s22
	v_lshrrev_b32_e32 v1, 31, v0
	v_add_u32_e32 v165, v0, v1
	v_mad_u64_u32 v[16:17], s[0:1], v165, s23, v[102:103]
	v_lshlrev_b32_e32 v249, 2, v16
	v_add_u32_e32 v249, 0x20200, v249
	v_readlane_b32 s36, v253, 1
	v_ashrrev_i32_e32 v17, 31, v16
	v_readlane_b32 s42, v253, 7
	v_readlane_b32 s43, v253, 8
	v_lshlrev_b32_e32 v106, 4, v165
	v_and_b32_e32 v46, 0x7f0, v106
	v_lshl_add_u64 v[8:9], v[16:17], 2, s[42:43]
	v_add_co_u32_e32 v4, vcc, s24, v8
	v_lshl_add_u64 v[10:11], v[8:9], 0, s[10:11]
	s_nop 0
	v_addc_co_u32_e32 v5, vcc, 0, v9, vcc
	v_add_co_u32_e32 v12, vcc, s25, v8
	ds_read_b128 v[20:23], v249 offset:16
	ds_read_b128 v[0:3], v249
	v_addc_co_u32_e32 v13, vcc, 0, v9, vcc
	ds_read_b128 v[4:7], v249 offset:6144
	s_nop 0
	ds_read_b128 v[24:27], v249 offset:6160
	v_lshl_add_u64 v[10:11], v[8:9], 0, s[12:13]
	v_lshl_add_u64 v[18:19], v[8:9], 0, s[14:15]
	v_add_co_u32_e32 v8, vcc, s26, v8
	v_lshl_add_u64 v[36:37], v[16:17], 1, s[2:3]
	s_nop 0
	v_addc_co_u32_e32 v9, vcc, 0, v9, vcc
	v_or_b32_e32 v38, 1, v106
	v_mad_i64_i32 v[16:17], s[0:1], v106, s27, v[36:37]
	v_mad_i64_i32 v[38:39], s[0:1], v38, s27, v[36:37]
	v_cmp_ne_u32_e32 vcc, 0, v46
	v_cmp_eq_u32_e64 s[4:5], 0, v46
	ds_read_b128 v[12:15], v249 offset:12288
	s_nop 0
	ds_read_b128 v[28:31], v249 offset:12304
	s_nop 0
	ds_read_b128 v[8:11], v249 offset:18432
	s_nop 0
	ds_read_b128 v[32:35], v249 offset:18448
	v_subbrev_co_u32_e32 v38, vcc, 0, v106, vcc
	v_cndmask_b32_e64 v46, -2, 0, s[4:5]
	v_or_b32_e32 v44, 2, v106
	v_mad_i64_i32 v[38:39], s[0:1], v38, s27, v[36:37]
	v_add_u32_e32 v46, v46, v106
	v_mad_i64_i32 v[38:39], s[0:1], v44, s27, v[36:37]
	v_or_b32_e32 v44, 3, v106
	v_mad_i64_i32 v[46:47], s[0:1], v46, s27, v[36:37]
	v_mad_i64_i32 v[44:45], s[0:1], v44, s27, v[36:37]
	v_cndmask_b32_e64 v46, -3, 0, s[4:5]
	v_add_u32_e32 v46, v46, v106
	v_or_b32_e32 v38, 4, v106
	v_or_b32_e32 v44, 5, v106
	v_mad_i64_i32 v[46:47], s[0:1], v46, s27, v[36:37]
	v_mad_i64_i32 v[38:39], s[0:1], v38, s27, v[36:37]
	v_mad_i64_i32 v[44:45], s[0:1], v44, s27, v[36:37]
	v_or_b32_e32 v38, 6, v106
	v_or_b32_e32 v44, 7, v106
	v_mad_i64_i32 v[38:39], s[0:1], v38, s27, v[36:37]
	v_mad_i64_i32 v[44:45], s[0:1], v44, s27, v[36:37]
	v_or_b32_e32 v38, 8, v106
	v_or_b32_e32 v44, 9, v106
	v_mad_i64_i32 v[38:39], s[0:1], v38, s27, v[36:37]
	v_mad_i64_i32 v[44:45], s[0:1], v44, s27, v[36:37]
	v_or_b32_e32 v38, 10, v106
	v_or_b32_e32 v44, 11, v106
	v_mad_i64_i32 v[38:39], s[0:1], v38, s27, v[36:37]
	v_mad_i64_i32 v[44:45], s[0:1], v44, s27, v[36:37]
	v_or_b32_e32 v38, 12, v106
	v_or_b32_e32 v44, 13, v106
	v_mad_i64_i32 v[38:39], s[0:1], v38, s27, v[36:37]
	v_mad_i64_i32 v[44:45], s[0:1], v44, s27, v[36:37]
	v_or_b32_e32 v38, 14, v106
	v_or_b32_e32 v44, 15, v106
	v_mad_i64_i32 v[38:39], s[0:1], v38, s27, v[36:37]
	v_mad_i64_i32 v[36:37], s[0:1], v44, s27, v[36:37]
	s_nop 0
	v_mad_u64_u32 v[108:109], s[0:1], v165, -3, v[96:97]
	v_subrev_co_u32_e32 v109, vcc, 1, v108
	v_cmp_gt_i32_e64 s[0:1], 2, v108
	s_nop 0
	v_cndmask_b32_e32 v166, 1.0, v97, vcc
	v_readlane_b32 s37, v253, 2
	v_readlane_b32 s38, v253, 3
	v_readlane_b32 s39, v253, 4
	v_readlane_b32 s40, v253, 5
	v_readlane_b32 s41, v253, 6
	v_readlane_b32 s44, v253, 9
	v_readlane_b32 s45, v253, 10
	v_readlane_b32 s46, v253, 11
	v_readlane_b32 s47, v253, 12
	v_readlane_b32 s48, v253, 13
	v_readlane_b32 s49, v253, 14
	v_readlane_b32 s50, v253, 15
	v_readlane_b32 s51, v253, 16
	s_cmp_eq_u32 s101, 1
	s_cbranch_scc1 .Lqk_w16
	s_cmp_eq_u32 s101, 2
	s_cbranch_scc1 .Lqk_w32
	s_waitcnt vmcnt(0)
	s_branch .Lqk_wd

; __device__ __forceinline__ void phase_qkv(const Args& a) {
;     ...
;     for (int item = blockIdx.x * 8 + wave; item < 6144; item += gridDim.x * 8) {
;         const int part = item % 3, rg = item / 3, rowA = rg * 16, pos0 = rowA & 2047, ch0 = part * 512 + 8 * lane;
;         float w[4][8];
; #pragma unroll
;         for (int i = 0; i < 4; ++i) { const f32x4 w0 = *(const f32x4*)(cw + i * 1536 + ch0), w1 = *(const f32x4*)(cw + i * 1536 + ch0 + 4);
;             w[i][0] = w0[0]; w[i][1] = w0[1]; w[i][2] = w0[2]; w[i][3] = w0[3]; w[i][4] = w1[0]; w[i][5] = w1[1]; w[i][6] = w1[2]; w[i][7] = w1[3]; }
;         u32x4 R[19];
; #pragma unroll
;         for (int j = 0; j < 19; ++j) { const int dr = j - 3; const int rr = (pos0 + dr >= 0) ? rowA + dr : rowA; R[j] = *(const u32x4*)(proj + (size_t)rr * NPROJ + ch0); }
.Lqk_wd:
	v_mov_b64_e32 v[168:169], v[172:173]
	v_mov_b64_e32 v[170:171], v[174:175]
	v_mov_b64_e32 v[146:147], v[176:177]
	v_mov_b64_e32 v[148:149], v[178:179]
	v_mov_b64_e32 v[122:123], v[180:181]
	v_mov_b64_e32 v[124:125], v[182:183]
	v_mov_b64_e32 v[16:17], v[184:185]
	v_mov_b64_e32 v[18:19], v[186:187]
	v_mov_b64_e32 v[40:41], v[188:189]
	v_mov_b64_e32 v[42:43], v[190:191]
	v_mov_b64_e32 v[48:49], v[192:193]
	v_mov_b64_e32 v[50:51], v[194:195]
	v_mov_b64_e32 v[56:57], v[196:197]
	v_mov_b64_e32 v[58:59], v[198:199]
	v_mov_b64_e32 v[64:65], v[200:201]
	v_mov_b64_e32 v[66:67], v[202:203]
	v_mov_b64_e32 v[72:73], v[204:205]
	v_mov_b64_e32 v[74:75], v[206:207]
	v_mov_b64_e32 v[80:81], v[208:209]
	v_mov_b64_e32 v[82:83], v[210:211]
	v_mov_b64_e32 v[88:89], v[212:213]
	v_mov_b64_e32 v[90:91], v[214:215]
	v_mov_b64_e32 v[92:93], v[216:217]
	v_mov_b64_e32 v[94:95], v[218:219]
	v_mov_b64_e32 v[84:85], v[220:221]
	v_mov_b64_e32 v[86:87], v[222:223]
	v_mov_b64_e32 v[76:77], v[224:225]
	v_mov_b64_e32 v[78:79], v[226:227]
	v_mov_b64_e32 v[68:69], v[228:229]
	v_mov_b64_e32 v[70:71], v[230:231]
	v_mov_b64_e32 v[60:61], v[232:233]
	v_mov_b64_e32 v[62:63], v[234:235]
	v_mov_b64_e32 v[52:53], v[236:237]
	v_mov_b64_e32 v[54:55], v[238:239]
	v_mov_b64_e32 v[44:45], v[240:241]
	v_mov_b64_e32 v[46:47], v[242:243]
	v_mov_b64_e32 v[36:37], v[244:245]
	v_mov_b64_e32 v[38:39], v[246:247]
	s_cmp_eq_u32 s88, 1
	s_cselect_b32 s101, 2, 1
	s_add_u32 s91, s90, s20
	s_cmp_lt_u32 s88, 2
	s_cbranch_scc0 .Lqk_nopf
	s_mul_hi_u32 s92, s91, 0x55555556
	s_mul_i32 s93, s92, 3
	s_sub_u32 s93, s91, s93
	s_mul_i32 s94, s92, 0x14000
	s_lshl_b32 s95, s93, 10
	s_add_u32 s94, s94, s95
	s_add_u32 s96, s2, s94
	s_addc_u32 s97, s3, 0
	s_and_b32 s95, s92, 0x7f
	s_cmp_eq_u32 s95, 0
	s_cselect_b32 s95, 0, 0x1400
	s_mul_i32 s100, s95, 3
	s_sub_u32 s98, s96, s100
	s_subb_u32 s99, s97, 0
	global_load_dwordx4 v[172:175], v248, s[98:99]
	s_add_u32 s98, s98, s95
	s_addc_u32 s99, s99, 0
	global_load_dwordx4 v[176:179], v248, s[98:99]
	s_add_u32 s98, s98, s95
	s_addc_u32 s99, s99, 0
	global_load_dwordx4 v[180:183], v248, s[98:99]
	global_load_dwordx4 v[184:187], v248, s[96:97]
	s_add_u32 s96, s96, 0x1400
	s_addc_u32 s97, s97, 0
	global_load_dwordx4 v[188:191], v248, s[96:97]
	s_add_u32 s96, s96, 0x1400
	s_addc_u32 s97, s97, 0
	global_load_dwordx4 v[192:195], v248, s[96:97]
	s_add_u32 s96, s96, 0x1400
	s_addc_u32 s97, s97, 0
	global_load_dwordx4 v[196:199], v248, s[96:97]
	s_add_u32 s96, s96, 0x1400
	s_addc_u32 s97, s97, 0
	global_load_dwordx4 v[200:203], v248, s[96:97]
	s_add_u32 s96, s96, 0x1400
	s_addc_u32 s97, s97, 0
	global_load_dwordx4 v[204:207], v248, s[96:97]
	s_add_u32 s96, s96, 0x1400
	s_addc_u32 s97, s97, 0
	global_load_dwordx4 v[208:211], v248, s[96:97]
	s_add_u32 s96, s96, 0x1400
	s_addc_u32 s97, s97, 0
	global_load_dwordx4 v[212:215], v248, s[96:97]
	s_add_u32 s96, s96, 0x1400
	s_addc_u32 s97, s97, 0
	global_load_dwordx4 v[216:219], v248, s[96:97]
	s_add_u32 s96, s96, 0x1400
	s_addc_u32 s97, s97, 0
	global_load_dwordx4 v[220:223], v248, s[96:97]
	s_add_u32 s96, s96, 0x1400
	s_addc_u32 s97, s97, 0
	global_load_dwordx4 v[224:227], v248, s[96:97]
	s_add_u32 s96, s96, 0x1400
	s_addc_u32 s97, s97, 0
	global_load_dwordx4 v[228:231], v248, s[96:97]
	s_add_u32 s96, s96, 0x1400
	s_addc_u32 s97, s97, 0
	global_load_dwordx4 v[232:235], v248, s[96:97]
	s_add_u32 s96, s96, 0x1400
	s_addc_u32 s97, s97, 0
	global_load_dwordx4 v[236:239], v248, s[96:97]
	s_add_u32 s96, s96, 0x1400
	s_addc_u32 s97, s97, 0
	global_load_dwordx4 v[240:243], v248, s[96:97]
	s_add_u32 s96, s96, 0x1400
	s_addc_u32 s97, s97, 0
	global_load_dwordx4 v[244:247], v248, s[96:97]

; __device__ __forceinline__ void phase_qkv(const Args& a) {
;     ...
;         if (part > 0) {
;             bf16_t* tb = (bf16_t*)(a.ws + (part == 1 ? WS_KT : WS_VT)) + ((size_t)(rg >> 2) * 512 + 8 * lane) * 64 + (rg & 3) * 16;
; #pragma unroll
;             for (int e = 0; e < 8; ++e) { u32x4 o0, o1;
; #pragma unroll
;                 for (int pp = 0; pp < 8; ++pp) { const unsigned A = yb[2 * pp][e >> 1], B = yb[2 * pp + 1][e >> 1];
;                     const unsigned v = (e & 1) ? ((A >> 16) | (B & 0xffff0000u)) : ((A & 0xffffu) | (B << 16));
;                     if (pp < 4) o0[pp] = v; else o1[pp - 4] = v; }
;                 *(u32x4*)(tb + e * 64) = o0; *(u32x4*)(tb + e * 64 + 8) = o1; }
.LBB0_194:
	s_or_b64 exec, exec, s[4:5]
	v_cmp_lt_i32_e32 vcc, 0, v108
	s_and_saveexec_b64 s[0:1], vcc
	s_cbranch_execz .LBB0_129
	v_lshrrev_b32_e32 v249, 4, v248
	v_add_u32_e32 v249, v165, v249
	v_and_b32_e32 v249, 3, v249
	v_lshl_add_u32 v249, v249, 5, v100
	v_bfe_u32 v250, v165, 2, 1
	v_lshl_add_u32 v250, v250, 16, v249
	s_barrier
	v_cmp_eq_u32_e32 vcc, 0, v109
	v_ashrrev_i32_e32 v6, 2, v165
	v_ashrrev_i32_e32 v7, 31, v6
	v_cndmask_b32_e32 v98, v163, v164, vcc
	v_lshl_add_u64 v[4:5], s[16:17], 0, v[98:99]
	v_lshlrev_b64 v[6:7], 16, v[6:7]
	v_lshl_add_u64 v[4:5], v[4:5], 0, v[6:7]
	v_and_b32_e32 v6, 48, v106
	v_lshl_add_u64 v[4:5], v[4:5], 0, v[100:101]
	v_lshlrev_b32_e32 v98, 1, v6
	v_lshl_add_u64 v[12:13], v[4:5], 0, v[98:99]
	v_and_b32_e32 v4, 0xffff, v16
	v_and_b32_e32 v5, 0xffff, v48
	v_and_b32_e32 v6, 0xffff, v64
	v_and_b32_e32 v7, 0xffff, v80
	v_and_b32_e32 v11, 0xffff, v44
	v_lshl_or_b32 v4, v40, 16, v4
	v_lshl_or_b32 v5, v56, 16, v5
	v_lshl_or_b32 v6, v72, 16, v6
	v_lshl_or_b32 v7, v88, 16, v7
	v_and_b32_e32 v8, 0xffff, v92
	v_and_b32_e32 v9, 0xffff, v76
	v_and_b32_e32 v10, 0xffff, v60
	v_lshl_or_b32 v11, v0, 16, v11
	v_lshl_or_b32 v8, v84, 16, v8
	v_lshl_or_b32 v9, v68, 16, v9
	v_lshl_or_b32 v10, v52, 16, v10
	ds_write_b128 v250, v[4:7]
	ds_write_b128 v250, v[8:11] offset:16
	s_nop 0
	v_lshrrev_b32_e32 v4, 16, v16
	v_lshrrev_b32_e32 v5, 16, v48
	v_lshrrev_b32_e32 v6, 16, v64
	v_lshrrev_b32_e32 v7, 16, v80
	v_lshrrev_b32_e32 v11, 16, v44
	v_and_or_b32 v4, v40, s28, v4
	v_and_or_b32 v5, v56, s28, v5
	v_and_or_b32 v6, v72, s28, v6
	v_and_or_b32 v7, v88, s28, v7
	v_lshrrev_b32_e32 v8, 16, v92
	v_lshrrev_b32_e32 v9, 16, v76
	v_lshrrev_b32_e32 v10, 16, v60
	v_and_or_b32 v11, v0, s28, v11
	v_and_b32_e32 v0, 0xffff, v17
	v_and_or_b32 v8, v84, s28, v8
	v_and_or_b32 v9, v68, s28, v9
	v_and_or_b32 v10, v52, s28, v10
	ds_write_b128 v250, v[4:7] offset:128
	ds_write_b128 v250, v[8:11] offset:144
	s_nop 0
	v_lshl_or_b32 v4, v41, 16, v0
	v_and_b32_e32 v0, 0xffff, v49
	v_lshl_or_b32 v5, v57, 16, v0
	v_and_b32_e32 v0, 0xffff, v65
	v_lshl_or_b32 v6, v73, 16, v0
	v_and_b32_e32 v0, 0xffff, v81
	v_lshl_or_b32 v7, v89, 16, v0
	v_and_b32_e32 v0, 0xffff, v93
	v_lshl_or_b32 v8, v85, 16, v0
	v_and_b32_e32 v0, 0xffff, v77
	v_lshl_or_b32 v9, v69, 16, v0
	v_and_b32_e32 v0, 0xffff, v61
	v_lshl_or_b32 v10, v53, 16, v0
	v_and_b32_e32 v0, 0xffff, v45
	v_lshl_or_b32 v11, v1, 16, v0
	v_lshrrev_b32_e32 v0, 16, v17
	ds_write_b128 v250, v[4:7] offset:256
	ds_write_b128 v250, v[8:11] offset:272
	s_nop 0
	v_and_or_b32 v4, v41, s28, v0
	v_lshrrev_b32_e32 v0, 16, v49
	v_and_or_b32 v5, v57, s28, v0
	v_lshrrev_b32_e32 v0, 16, v65
	v_and_or_b32 v6, v73, s28, v0
	v_lshrrev_b32_e32 v0, 16, v81
	v_and_or_b32 v7, v89, s28, v0
	v_lshrrev_b32_e32 v0, 16, v93
	v_and_or_b32 v8, v85, s28, v0
	v_lshrrev_b32_e32 v0, 16, v77
	v_and_or_b32 v9, v69, s28, v0
	v_lshrrev_b32_e32 v0, 16, v61
	v_and_or_b32 v10, v53, s28, v0
	v_lshrrev_b32_e32 v0, 16, v45
	v_and_or_b32 v11, v1, s28, v0
	v_and_b32_e32 v0, 0xffff, v18
	ds_write_b128 v250, v[4:7] offset:384
	ds_write_b128 v250, v[8:11] offset:400
	v_lshrrev_b32_e32 v1, 16, v79
	v_lshl_or_b32 v4, v42, 16, v0
	v_and_b32_e32 v0, 0xffff, v50
	v_lshl_or_b32 v5, v58, 16, v0
	v_and_b32_e32 v0, 0xffff, v66
	v_lshl_or_b32 v6, v74, 16, v0
	v_and_b32_e32 v0, 0xffff, v82
	v_lshl_or_b32 v7, v90, 16, v0
	v_and_b32_e32 v0, 0xffff, v94
	v_lshl_or_b32 v8, v86, 16, v0
	v_and_b32_e32 v0, 0xffff, v78
	v_lshl_or_b32 v9, v70, 16, v0
	v_and_b32_e32 v0, 0xffff, v62
	v_lshl_or_b32 v10, v54, 16, v0
	v_and_b32_e32 v0, 0xffff, v46
	v_lshl_or_b32 v11, v2, 16, v0
	v_lshrrev_b32_e32 v0, 16, v18
	ds_write_b128 v250, v[4:7] offset:512
	ds_write_b128 v250, v[8:11] offset:528
	v_and_or_b32 v1, v71, s28, v1
	v_and_or_b32 v4, v42, s28, v0
	v_lshrrev_b32_e32 v0, 16, v50
	v_and_or_b32 v5, v58, s28, v0
	v_lshrrev_b32_e32 v0, 16, v66
	v_and_or_b32 v6, v74, s28, v0
	v_lshrrev_b32_e32 v0, 16, v82
	v_and_or_b32 v7, v90, s28, v0
	v_lshrrev_b32_e32 v0, 16, v94
	v_and_or_b32 v8, v86, s28, v0
	v_lshrrev_b32_e32 v0, 16, v78
	v_and_or_b32 v9, v70, s28, v0
	v_lshrrev_b32_e32 v0, 16, v62
	v_and_or_b32 v10, v54, s28, v0
	v_lshrrev_b32_e32 v0, 16, v46
	v_and_or_b32 v11, v2, s28, v0
	v_and_b32_e32 v0, 0xffff, v19
	ds_write_b128 v250, v[4:7] offset:640
	ds_write_b128 v250, v[8:11] offset:656
	v_lshrrev_b32_e32 v2, 16, v63
	v_lshl_or_b32 v4, v43, 16, v0
	v_and_b32_e32 v0, 0xffff, v51
	v_lshl_or_b32 v5, v59, 16, v0
	v_and_b32_e32 v0, 0xffff, v67
	v_lshl_or_b32 v6, v75, 16, v0
	v_and_b32_e32 v0, 0xffff, v83
	v_lshl_or_b32 v7, v91, 16, v0
	v_and_b32_e32 v0, 0xffff, v95
	v_lshl_or_b32 v8, v87, 16, v0
	v_and_b32_e32 v0, 0xffff, v79
	v_lshl_or_b32 v9, v71, 16, v0
	v_and_b32_e32 v0, 0xffff, v63
	v_lshl_or_b32 v10, v55, 16, v0
	v_and_b32_e32 v0, 0xffff, v47
	v_lshl_or_b32 v11, v3, 16, v0
	v_lshrrev_b32_e32 v0, 16, v19
	ds_write_b128 v250, v[4:7] offset:768
	ds_write_b128 v250, v[8:11] offset:784
	v_and_or_b32 v2, v55, s28, v2
	v_and_or_b32 v4, v43, s28, v0
	v_lshrrev_b32_e32 v0, 16, v51
	v_and_or_b32 v5, v59, s28, v0
	v_lshrrev_b32_e32 v0, 16, v67
	v_and_or_b32 v6, v75, s28, v0
	v_lshrrev_b32_e32 v0, 16, v83
	v_and_or_b32 v7, v91, s28, v0
	v_lshrrev_b32_e32 v0, 16, v95
	v_lshrrev_b32_e32 v8, 16, v47
	v_and_or_b32 v0, v87, s28, v0
	v_and_or_b32 v3, v3, s28, v8
	ds_write_b128 v250, v[4:7] offset:896
	ds_write_b128 v250, v[0:3] offset:912
	s_waitcnt lgkmcnt(0)
	s_barrier
; __device__ __forceinline__ void phase_qkv(const Args& a) {
;     ...
;         if (part > 0) {
;             bf16_t* tb = (bf16_t*)(a.ws + (part == 1 ? WS_KT : WS_VT)) + ((size_t)(rg >> 2) * 512 + 8 * lane) * 64 + (rg & 3) * 16;
; #pragma unroll
;             for (int e = 0; e < 8; ++e) { u32x4 o0, o1;
; #pragma unroll
;                 for (int pp = 0; pp < 8; ++pp) { const unsigned A = yb[2 * pp][e >> 1], B = yb[2 * pp + 1][e >> 1];
;                     const unsigned v = (e & 1) ? ((A >> 16) | (B & 0xffff0000u)) : ((A & 0xffffu) | (B << 16));
;                     if (pp < 4) o0[pp] = v; else o1[pp - 4] = v; }
;                 *(u32x4*)(tb + e * 64) = o0; *(u32x4*)(tb + e * 64 + 8) = o1; }
	v_lshrrev_b32_e32 v64, 4, v248
	v_lshrrev_b32_e32 v65, 3, v64
	v_and_b32_e32 v66, 1, v64
	v_lshlrev_b32_e32 v66, 4, v66
	v_lshl_add_u32 v66, v65, 7, v66
	s_and_b32 s92, s86, 7
	s_lshl_b32 s92, s92, 14
	v_add_u32_e32 v66, s92, v66
	v_bfe_u32 v65, v64, 1, 2
	v_lshl_add_u32 v68, v65, 5, v66
	v_add_u32_e32 v67, 1, v65
	v_and_b32_e32 v67, 3, v67
	v_lshl_add_u32 v69, v67, 5, v66
	v_add_u32_e32 v67, 2, v65
	v_and_b32_e32 v67, 3, v67
	v_lshl_add_u32 v70, v67, 5, v66
	v_add_u32_e32 v67, 3, v65
	v_and_b32_e32 v67, 3, v67
	v_lshl_add_u32 v71, v67, 5, v66
	ds_read_b128 v[0:3], v68
	ds_read_b128 v[4:7], v69 offset:1024
	ds_read_b128 v[8:11], v70 offset:2048
	ds_read_b128 v[12:15], v71 offset:3072
	ds_read_b128 v[16:19], v68 offset:4096
	ds_read_b128 v[20:23], v69 offset:5120
	ds_read_b128 v[24:27], v70 offset:6144
	ds_read_b128 v[28:31], v71 offset:7168
	ds_read_b128 v[32:35], v68 offset:8192
	ds_read_b128 v[36:39], v69 offset:9216
	ds_read_b128 v[40:43], v70 offset:10240
	ds_read_b128 v[44:47], v71 offset:11264
	ds_read_b128 v[48:51], v68 offset:12288
	ds_read_b128 v[52:55], v69 offset:13312
	ds_read_b128 v[56:59], v70 offset:14336
	ds_read_b128 v[60:63], v71 offset:15360
	s_mov_b32 s94, 0x4000000
	s_cmp_eq_u32 s88, 1
	s_cselect_b32 s94, 0x2000000, s94
	s_lshr_b32 s95, s86, 3
	s_lshl_b32 s95, s95, 17
	s_add_u32 s94, s94, s95
	s_add_u32 s94, s94, s92
	s_add_u32 s96, s16, s94
	s_addc_u32 s97, s17, 0
	s_waitcnt lgkmcnt(0)
	global_store_dwordx4 v248, v[0:3], s[96:97]
	global_store_dwordx4 v248, v[4:7], s[96:97] offset:1024
	global_store_dwordx4 v248, v[8:11], s[96:97] offset:2048
	global_store_dwordx4 v248, v[12:15], s[96:97] offset:3072
	s_add_u32 s96, s96, 0x1000
	s_addc_u32 s97, s97, 0
	global_store_dwordx4 v248, v[16:19], s[96:97]
	global_store_dwordx4 v248, v[20:23], s[96:97] offset:1024
	global_store_dwordx4 v248, v[24:27], s[96:97] offset:2048
	global_store_dwordx4 v248, v[28:31], s[96:97] offset:3072
	s_add_u32 s96, s96, 0x1000
	s_addc_u32 s97, s97, 0
	global_store_dwordx4 v248, v[32:35], s[96:97]
	global_store_dwordx4 v248, v[36:39], s[96:97] offset:1024
	global_store_dwordx4 v248, v[40:43], s[96:97] offset:2048
	global_store_dwordx4 v248, v[44:47], s[96:97] offset:3072
	s_add_u32 s96, s96, 0x1000
	s_addc_u32 s97, s97, 0
	global_store_dwordx4 v248, v[48:51], s[96:97]
	global_store_dwordx4 v248, v[52:55], s[96:97] offset:1024
	global_store_dwordx4 v248, v[56:59], s[96:97] offset:2048
	global_store_dwordx4 v248, v[60:63], s[96:97] offset:3072
	s_branch .LBB0_129
